# phase-0 items first needed in phase 3 or later (Tglu/Tout/Bpow/Cpow/misc, item pairs 992..3968) deferred to the tail of phase 2 on the 224 workgroups that have no context-projection unit (variable str
# speedup vs baseline: 1.0334x; 1.0125x over previous
.LBB0_5:
	s_or_b64 exec, exec, s[4:5]
	s_mov_b32 s101, 0
	s_mov_b32 s98, 0x100
	s_mov_b32 s100, 0x60
	s_mov_b32 s99, s81
.Lp0_enter:
	s_load_dwordx16 s[52:67], s[0:1], 0x0
	s_load_dwordx16 s[4:19], s[0:1], 0x40
	s_load_dwordx16 s[36:51], s[0:1], 0x80
	s_cmp_ge_i32 s99, s100
	s_waitcnt lgkmcnt(0)
	v_writelane_b32 v241, s4, 18
	s_nop 1
	v_writelane_b32 v241, s5, 19
	v_writelane_b32 v241, s6, 20
	v_writelane_b32 v241, s7, 21
	v_writelane_b32 v241, s8, 22
	v_writelane_b32 v241, s9, 23
	v_writelane_b32 v241, s10, 24
	v_writelane_b32 v241, s11, 25
	v_writelane_b32 v241, s12, 26
	v_writelane_b32 v241, s13, 27
	v_writelane_b32 v241, s14, 28
	v_writelane_b32 v241, s15, 29
	v_writelane_b32 v241, s16, 30
	v_writelane_b32 v241, s17, 31
	v_writelane_b32 v241, s18, 32
	v_writelane_b32 v241, s19, 33
	v_writelane_b32 v241, s36, 34
	s_nop 1
	v_writelane_b32 v241, s37, 35
	v_writelane_b32 v241, s38, 36
	v_writelane_b32 v241, s39, 37
	v_writelane_b32 v241, s40, 38
	v_writelane_b32 v241, s41, 39
	v_writelane_b32 v241, s42, 40
	v_writelane_b32 v241, s43, 41
	v_writelane_b32 v241, s44, 42
	v_writelane_b32 v241, s45, 43
	v_writelane_b32 v241, s46, 44
	v_writelane_b32 v241, s47, 45
	v_writelane_b32 v241, s48, 46
	v_writelane_b32 v241, s49, 47
	v_writelane_b32 v241, s50, 48
	v_writelane_b32 v241, s51, 49
	v_writelane_b32 v241, s81, 50
	v_writelane_b32 v241, s82, 51
	s_nop 1
	v_writelane_b32 v241, s83, 52
	v_writelane_b32 v241, s96, 53
	s_nop 1
	v_writelane_b32 v241, s97, 54
	v_writelane_b32 v241, s52, 55
	s_nop 1
	v_writelane_b32 v241, s53, 56
	v_writelane_b32 v241, s54, 57
	v_writelane_b32 v240, s61, 0
	v_writelane_b32 v241, s55, 58
	v_writelane_b32 v240, s62, 1
	v_writelane_b32 v241, s56, 59
	v_writelane_b32 v240, s63, 2
	v_writelane_b32 v241, s57, 60
	v_writelane_b32 v240, s64, 3
	v_writelane_b32 v241, s58, 61
	v_writelane_b32 v240, s65, 4
	v_writelane_b32 v241, s59, 62
	v_writelane_b32 v240, s66, 5
	v_writelane_b32 v241, s60, 63
	v_writelane_b32 v240, s67, 6
	s_cbranch_scc1 .LBB0_92
	s_load_dwordx16 s[4:19], s[0:1], 0xc0
	v_writelane_b32 v240, s78, 7
	s_waitcnt lgkmcnt(0)
	s_mov_b32 s7, 0x3fe45f30
	v_lshrrev_b32_e32 v1, 8, v193
	v_writelane_b32 v240, s79, 8
	s_add_u32 s2, s14, 0x1000
	s_addc_u32 s3, s15, 0
	v_writelane_b32 v240, s2, 9
	s_mov_b32 s8, 0
	v_mov_b32_e32 v35, 0
	v_writelane_b32 v240, s3, 10
	s_add_u32 s2, s14, 0x2000
	s_addc_u32 s3, s15, 0
	v_writelane_b32 v240, s2, 11
	v_lshl_add_u32 v82, v1, 16, 0
	s_mov_b32 s96, 0x6dc9c883
	v_writelane_b32 v240, s3, 12
	s_add_u32 s2, s14, 0x3000
	s_addc_u32 s3, s15, 0
	v_writelane_b32 v240, s2, 13
	s_mov_b32 s4, 0x54442d18
	s_lshl_b32 s33, s98, 5
	v_writelane_b32 v240, s3, 14
	v_writelane_b32 v240, s6, 15
	s_lshl_b32 s2, s99, 1
	v_add_u32_e32 v2, s2, v1
	v_writelane_b32 v240, s7, 16
	s_mov_b32 s7, 0xbff921fb
	v_writelane_b32 v240, s6, 17
	v_add_u32_e32 v83, 0xfffff540, v2
	v_lshlrev_b32_e32 v2, 4, v1
	v_writelane_b32 v240, s7, 18
	v_writelane_b32 v240, s8, 19
	s_lshl_b32 s3, s98, 1
	v_lshlrev_b32_e32 v84, 4, v83
	v_writelane_b32 v240, s9, 20
	v_add_u32_e32 v85, 0x8100, v82
	v_add_u16_e32 v86, s2, v1
	v_add_u32_e32 v87, 0x4100, v82
	v_lshl_add_u32 v88, s99, 5, v2
	v_mov_b32_e32 v106, v35
	v_mov_b32_e32 v107, v35
	v_mov_b32_e32 v108, v35
	v_mov_b32_e32 v109, v35
	s_mov_b32 s34, 0x3fb8aa3b
	s_mov_b32 s35, 0xc2ce8ed0
	s_mov_b32 s68, 0x42b17218
	s_mov_b32 s97, 0x3fc45f30
	s_mov_b32 s5, 0xc01921fb
	s_brev_b32 s69, 18
	s_mov_b32 s70, 0xfe5163ab
	s_mov_b32 s71, 0x3c439041
	s_mov_b32 s72, 0xdb629599
	s_mov_b32 s73, 0xf534ddc0
	s_mov_b32 s74, 0xfc2757d1
	s_mov_b32 s75, 0x4e441529
	s_mov_b32 s76, 0xa2f9836e
	s_mov_b32 s77, 0x3fc90fda
	s_mov_b32 s78, 0x3f22f983
	s_mov_b32 s79, 0xbfc90fda
	v_mov_b32_e32 v89, 0x3c0881c4
	v_mov_b32_e32 v90, 0xbab64f3b
	s_brev_b32 s80, 1
	s_mov_b32 s2, s99
	s_movk_i32 s81, 0x1f8
	s_movk_i32 s83, 0x7fff
	v_mov_b32_e32 v91, 0x7f800000
	v_not_b32_e32 v92, 63
	v_not_b32_e32 v93, 31
	v_mov_b32_e32 v94, 0x7fc00000
	v_mov_b32_e32 v95, 1
	v_mov_b32_e32 v96, 0x40100000
	v_mov_b32_e32 v97, 0x3ff00000
	v_mov_b32_e32 v36, 0xfca7ab0c
	v_mov_b32_e32 v37, 0x3e928af3
	v_mov_b32_e32 v38, 0x623fde64
	v_mov_b32_e32 v39, 0x3ec71dee
	v_mov_b32_e32 v40, 0x7c89e6b0
	v_mov_b32_e32 v41, 0x3efa0199
	v_mov_b32_e32 v42, 0x14761f6e
	v_mov_b32_e32 v43, 0x3f2a01a0
	v_mov_b32_e32 v44, 0x1852b7b0
	v_mov_b32_e32 v45, 0x3f56c16c
	v_mov_b32_e32 v46, 0x11122322
	v_mov_b32_e32 v47, 0x3f811111
	v_mov_b32_e32 v48, 0x555502a1
	v_mov_b32_e32 v49, 0x3fa55555
	v_mov_b32_e32 v50, 0x55555511
	v_mov_b32_e32 v51, 0x3fc55555
	v_mov_b32_e32 v52, 11
	v_mov_b32_e32 v53, 0x3fe00000
	v_mov_b32_e32 v98, 0x7ff00000
	v_mov_b32_e32 v54, 0x9037ab78
	v_mov_b32_e32 v55, 0x3e21eeb6
	v_mov_b32_e32 v56, 0xa17f65f6
	v_mov_b32_e32 v57, 0xbe927e4f
	v_mov_b32_e32 v58, 0x19f4ec90
	v_mov_b32_e32 v59, 0x3efa01a0
	v_mov_b32_e32 v60, 0x16c16967
	v_mov_b32_e32 v61, 0xbf56c16c
	v_mov_b32_e32 v62, 0x55555555
	v_mov_b32_e32 v64, 0xb42fdfa7
	v_mov_b32_e32 v65, 0xbe5ae600
	v_mov_b32_e32 v66, 0x796cde01
	v_mov_b32_e32 v67, 0x3ec71de3
	v_mov_b32_e32 v68, 0x19e83e5c
	v_mov_b32_e32 v69, 0xbf2a01a0
	v_mov_b32_e32 v70, 0x11110bb3
	v_mov_b32_e32 v99, 0x7ff80000
	v_mov_b32_e32 v100, 0x2000
	s_movk_i32 s82, 0x208
	s_mov_b32 s65, 0x3ff921fb
	s_mov_b32 s67, 0x3c91a626
	s_mov_b32 s64, 0x33145c07
	v_writelane_b32 v240, s10, 21
	v_writelane_b32 v240, s11, 22
	s_branch .LBB0_9

.LBB0_8:
	s_or_b64 exec, exec, s[6:7]
	s_load_dwordx2 s[6:7], s[0:1], 0x160
	v_add_u32_e32 v83, s3, v83
	v_add_u32_e32 v84, s33, v84
	v_add_u16_e32 v86, s3, v86
	v_add_u32_e32 v88, s33, v88
	s_waitcnt lgkmcnt(0)
	s_add_i32 s2, s2, s98
	s_cmp_lt_i32 s2, s100
	s_cbranch_scc0 .LBB0_91

.LBB0_92:
	s_load_dwordx2 s[6:7], s[0:1], 0x158
	s_load_dwordx8 s[36:43], s[0:1], 0x138
	s_cmp_eq_u32 s101, 0
	s_cbranch_scc1 .Lst_cont0
	s_waitcnt lgkmcnt(0)
	s_cmp_eq_u32 s101, 2
	s_cbranch_scc1 .Lst_b_to_p1
	s_cmp_eq_u32 s101, 5
	s_cbranch_scc1 .Lst_p2tail
	s_cmpk_lg_i32 s82, 0x100
	s_cselect_b64 s[0:1], -1, 0
	v_writelane_b32 v240, s0, 11
	v_writelane_b32 v240, s1, 12
	s_cmp_lt_i32 s81, 32
	s_cselect_b64 s[0:1], -1, 0
	s_branch .LBB0_179
.Lst_p2tail:
	s_cmpk_lg_i32 s82, 0x100
	s_cselect_b64 s[0:1], -1, 0
	v_writelane_b32 v240, s0, 11
	v_writelane_b32 v240, s1, 12
	s_branch .LBB0_262

.LBB0_156:
	s_or_b64 exec, exec, s[0:1]
	s_mov_b32 s100, 0x3e0
	s_add_u32 s99, s81, 0x100
	s_cmp_lt_u32 s81, 0x60
	s_cselect_b32 s99, s99, s81
	s_and_b32 vcc_lo, s81, 8
	s_cmp_eq_u32 vcc_lo, 0
	s_cbranch_scc1 .Lgrp_a
	s_mov_b32 s101, 2
	s_sub_u32 s0, s78, 0x160
	s_subb_u32 s1, s79, 0
	s_branch .Lp0_enter

.LBB0_251:
	v_mov_b32_e32 v8, v193
	s_andn2_b64 vcc, exec, s[0:1]
	v_readfirstlane_b32 s2, v8
	s_cbranch_vccz .Lctx_unit
	s_cmpk_lg_i32 s82, 0x100
	s_cbranch_scc1 .LBB0_262
	s_mov_b32 s101, 5
	s_mov_b32 s98, 0xe0
	s_sub_u32 s99, s81, 32
	s_add_u32 s99, s99, 0x3e0
	s_mov_b32 s100, 0xf81
	s_sub_u32 s0, s78, 0x160
	s_subb_u32 s1, s79, 0
	s_branch .Lp0_enter
.Lctx_unit:
	v_lshlrev_b32_e32 v0, 4, v8
	v_add_u32_e32 v1, 0x2000, v0
	v_ashrrev_i32_e32 v2, 31, v1
	v_lshrrev_b32_e32 v2, 22, v2
	v_add_u32_e32 v2, v1, v2
	v_ashrrev_i32_e32 v9, 10, v2
	v_mul_i32_i24_e32 v2, 0x400, v9
	v_sub_u32_e32 v1, v1, v2
	v_lshrrev_b32_e32 v2, 4, v1
	v_bitop3_b32 v1, v2, v1, 32 bitop3:0x6c
	v_ashrrev_i32_e32 v2, 31, v1
	v_lshrrev_b32_e32 v2, 26, v2
	v_add_u32_e32 v2, v1, v2
	v_lshlrev_b32_e32 v3, 3, v9
	v_ashrrev_i32_e32 v10, 6, v2
	v_and_b32_e32 v3, -16, v3
	s_and_b32 s1, s81, 3
	v_add_u32_e32 v3, v10, v3
	s_or_b32 s62, s1, 12
	v_and_b32_e32 v4, 3, v10
	s_mov_b32 s1, 0x1fffe0
	v_lshrrev_b32_e32 v5, 2, v3
	v_lshlrev_b32_e32 v6, 1, v3
	v_and_b32_e32 v2, 0xc0, v2
	v_and_or_b32 v4, v3, s1, v4
	v_and_b32_e32 v5, 4, v5
	v_and_b32_e32 v6, 24, v6
	v_sub_u32_e32 v1, v1, v2
	v_mov_b32_e32 v2, 1
	v_or3_b32 v4, v4, v5, v6
	v_lshlrev_b32_e32 v5, 5, v9
	v_ashrrev_i16_sdwa v1, v2, sext(v1) dst_sel:DWORD dst_unused:UNUSED_PAD src0_sel:DWORD src1_sel:BYTE_0
	v_and_b32_e32 v5, 32, v5
	v_bfe_i32 v11, v1, 0, 16
	v_add_lshl_u32 v1, v5, v11, 1
	v_lshl_add_u32 v128, v4, 11, v1
	v_lshl_add_u32 v130, v3, 11, v1
	v_bfe_i32 v1, v8, 27, 1
	v_lshrrev_b32_e32 v1, 22, v1
	v_add_u32_e32 v1, v0, v1
	v_and_b32_e32 v1, 0xfffffc00, v1
	v_sub_u32_e32 v0, v0, v1
	v_lshrrev_b32_e32 v1, 4, v0
	v_ashrrev_i32_e32 v3, 31, v8
	v_bitop3_b32 v0, v1, v0, 32 bitop3:0x6c
	v_lshrrev_b32_e32 v3, 26, v3
	v_ashrrev_i32_e32 v1, 31, v0
	v_add_u32_e32 v3, v8, v3
	v_lshrrev_b32_e32 v1, 26, v1
	v_ashrrev_i32_e32 v13, 6, v3
	v_add_u32_e32 v1, v0, v1
	v_lshlrev_b32_e32 v3, 3, v13
	v_ashrrev_i32_e32 v12, 6, v1
	v_and_b32_e32 v3, -16, v3
	v_add_u32_e32 v3, v12, v3
	s_ashr_i32 s5, s2, 6
	v_and_b32_e32 v4, 3, v12
	v_lshrrev_b32_e32 v5, 2, v3
	v_lshlrev_b32_e32 v6, 1, v3
	v_and_b32_e32 v1, 0xc0, v1
	v_readlane_b32 s8, v241, 0
	s_ashr_i32 s4, s2, 8
	s_lshl_b32 s0, s5, 10
	s_ashr_i32 s63, s81, 2
	v_and_or_b32 v4, v3, s1, v4
	v_and_b32_e32 v5, 4, v5
	v_and_b32_e32 v6, 24, v6
	v_sub_u32_e32 v0, v0, v1
	s_lshl_b32 s1, s62, 19
	v_readlane_b32 s14, v241, 6
	v_readlane_b32 s22, v241, 14
	v_or3_b32 v4, v4, v5, v6
	v_lshlrev_b32_e32 v5, 5, v13
	v_ashrrev_i16_sdwa v0, v2, sext(v0) dst_sel:DWORD dst_unused:UNUSED_PAD src0_sel:DWORD src1_sel:BYTE_0
	v_readlane_b32 s15, v241, 7
	v_readlane_b32 s23, v241, 15
	s_add_u32 s14, s22, s1
	v_and_b32_e32 v5, 32, v5
	v_bfe_i32 v14, v0, 0, 16
	v_readlane_b32 s10, v241, 2
	s_addc_u32 s15, s23, 0
	s_lshl_b32 s1, s63, 8
	v_add_lshl_u32 v0, v5, v14, 1
	v_readlane_b32 s11, v241, 3
	s_add_i32 s3, s0, 0
	s_add_i32 s10, s1, 0x8000
	v_lshl_add_u32 v132, v4, 11, v0
	s_add_i32 m0, s3, 0x10000
	s_ashr_i32 s11, s10, 31
	global_load_lds_dwordx4 v132, s[14:15]
	s_add_i32 m0, s3, 0x12000
	s_lshl_b64 s[10:11], s[10:11], 11
	s_add_u32 s34, s94, s10
	v_lshl_add_u32 v134, v3, 11, v0
	v_readlane_b32 s12, v241, 4
	global_load_lds_dwordx4 v128, s[14:15]
	s_addc_u32 s35, s95, s11
	s_mov_b32 m0, s3
	s_add_i32 s10, s3, 0x2000
	v_readlane_b32 s13, v241, 5
	global_load_lds_dwordx4 v134, s[34:35]
	s_mov_b32 m0, s10
	s_add_u32 s12, s14, 0x40000
	global_load_lds_dwordx4 v130, s[34:35]
	s_addc_u32 s13, s15, 0
	s_add_i32 m0, s3, 0x14000
	v_mov_b32_e32 v137, 0
	global_load_lds_dwordx4 v132, s[12:13]
	s_add_i32 m0, s3, 0x16000
	v_mov_b32_e32 v133, v137
	global_load_lds_dwordx4 v128, s[12:13]
	s_add_i32 s12, s1, 0x8080
	s_ashr_i32 s13, s12, 31
	s_lshl_b64 s[12:13], s[12:13], 11
	s_add_u32 s44, s94, s12
	s_addc_u32 s45, s95, s13
	s_add_i32 s11, s3, 0x4000
	s_mov_b32 m0, s11
	s_add_i32 s12, s3, 0x6000
	global_load_lds_dwordx4 v134, s[44:45]
	s_mov_b32 m0, s12
	v_mov_b32_e32 v129, v137
	global_load_lds_dwordx4 v130, s[44:45]
	v_mov_b32_e32 v135, v137
	v_mov_b32_e32 v131, v137
	s_mov_b32 s1, 0
	v_lshl_add_u64 v[6:7], s[14:15], 0, v[132:133]
	v_lshl_add_u64 v[4:5], s[14:15], 0, v[128:129]
	v_lshl_add_u64 v[2:3], s[34:35], 0, v[134:135]
	s_cmp_lg_u32 s4, 1
	v_lshl_add_u64 v[0:1], s[34:35], 0, v[130:131]
	v_readlane_b32 s9, v241, 1
	v_readlane_b32 s16, v241, 8
	v_readlane_b32 s17, v241, 9
	v_readlane_b32 s18, v241, 10
	v_readlane_b32 s19, v241, 11
	v_readlane_b32 s20, v241, 12
	v_readlane_b32 s21, v241, 13
	s_cbranch_scc1 .LBB0_255
	s_barrier
